# G7 K-loop: LDS-DMA staging rebalanced from 2/6/2/6 to 4/4/4/4 pieces per load part (A half-tiles staged one load part later), every wait vmcnt(4)
# baseline (speedup 1.0000x reference)
; #define PG8_STAGE(bufoff, gbase, voff, p64) do { _Pragma("unroll") for (int _i = 0; _i < 2; ++_i) { \
;         const char* _gb = (const char*)(gbase) + (size_t)_i * (p64); const unsigned _la = ldsbase + (unsigned)(bufoff) + (unsigned)_i * 8192u; \
;         asm volatile("s_mov_b32 m0, %0\n\ts_nop 0\n\tglobal_load_lds_dwordx4 %1, %2" :: "s"(_la), "v"(voff), "s"(_gb) : "memory"); } } while (0)
; #define PG8_WAIT_V(n) asm volatile("s_waitcnt vmcnt(" #n ")" ::: "memory")
; #define PG8_BAR __builtin_amdgcn_s_barrier()
; template <class Epi, class Sched>
; __device__ __forceinline__ void gemm_phase(LAS unsigned char* lds, const Sched& S, const Epi& E) {
;     ...
;     PG8_STAGE(PG8_SB(0, 0), cB, voffB, hB / 2); PG8_STAGE(PG8_SB(0, 1), cB + hB, voffB, hB / 2); PG8_STAGE(PG8_SA(0, 0), cA, voffA, hA / 2); PG8_STAGE(PG8_SA(0, 1), cA + hA, voffA, hA / 2);
;     if (wr == 1) PG8_BAR;
;     PG8_WAIT_V(2); PG8_BAR;
;     PG8_STAGE(PG8_SB(1, 0), cB + kstep, voffB, hB / 2); PG8_STAGE(PG8_SA(1, 0), cA + kstep, voffA, hA / 2); PG8_STAGE(PG8_SB(1, 1), cB + hB + kstep, voffB, hB / 2);
;     PG8_WAIT_V(6); PG8_BAR;
.LBB0_1479:
	s_add_u32 s12, s8, 0x8900000
	v_bfe_u32 v137, v0, 4, 2
	s_addc_u32 s13, s9, 0
	v_and_b32_e32 v136, 15, v0
	v_lshlrev_b32_e32 v1, 4, v137
	v_lshlrev_b32_e32 v0, 2, v0
	s_lshl_b32 s6, s6, 5
	v_lshl_or_b32 v1, v136, 6, v1
	s_lshl_b32 s8, s15, 13
	v_and_b32_e32 v0, 32, v0
	s_and_b32 s6, s6, 0x60
	s_lshl_b32 s47, s15, 6
	v_bitop3_b32 v2, v1, s8, v0 bitop3:0xde
	s_lshl_b32 s8, s6, 7
	v_bitop3_b32 v0, v1, s8, v0 bitop3:0xde
	s_add_u32 s8, s26, 0x80
	s_addc_u32 s9, s27, 0
	s_add_i32 s48, s34, 0x18000
	s_waitcnt vmcnt(2)
	s_barrier
	s_mov_b32 m0, s48
	s_nop 0
	global_load_lds_dwordx4 v135, s[8:9]
	s_add_u32 s8, s26, 0x20080
	s_addc_u32 s9, s27, 0
	s_add_i32 s49, s34, 0x1a000
	s_mov_b32 m0, s49
	s_nop 0
	global_load_lds_dwordx4 v135, s[8:9]
	s_add_i32 s50, s34, 0x8000
	s_add_i32 s51, s34, 0xa000
	s_add_u32 s8, s26, 0x40080
	s_addc_u32 s9, s27, 0
	s_add_i32 s52, s34, 0x1c000
	s_mov_b32 m0, s52
	s_nop 0
	global_load_lds_dwordx4 v135, s[8:9]
	s_add_u32 s8, s26, 0x60080
	s_addc_u32 s9, s27, 0
	s_add_i32 s53, s34, 0x1e000
	s_mov_b32 m0, s53
	s_nop 0
	global_load_lds_dwordx4 v135, s[8:9]
	s_waitcnt vmcnt(4)
	s_add_i32 s54, s34, 0xc000
	s_cmpk_lt_u32 s14, 0x100
	v_add_u32_e32 v0, 0, v0
	s_cselect_b64 s[14:15], -1, 0
	s_add_i32 s55, s34, 0xe000
	v_mov_b64_e32 v[128:129], 0xb00
	s_mov_b64 s[16:17], 0xaff
	v_mov_b64_e32 v[130:131], 0xaff
	v_add_u32_e32 v138, 0x10000, v0
	v_add_u32_e32 v139, 0x14000, v0
	v_add_u32_e32 v140, 0, v2
	v_add_u32_e32 v141, 0x18000, v0
	v_add_u32_e32 v142, 0x1c000, v0
	s_movk_i32 s56, 0x1600
	s_lshl_b32 s6, s6, 1
	s_mov_b32 s19, s7
	s_mov_b64 s[20:21], s[24:25]
	s_mov_b64 s[22:23], s[26:27]
	s_barrier
	s_waitcnt vmcnt(0)
	s_mov_b32 s99, -1
	s_branch .LBB0_1482

; #define PG8_STAGE(bufoff, gbase, voff, p64) do { _Pragma("unroll") for (int _i = 0; _i < 2; ++_i) { \
;         const char* _gb = (const char*)(gbase) + (size_t)_i * (p64); const unsigned _la = ldsbase + (unsigned)(bufoff) + (unsigned)_i * 8192u; \
;         asm volatile("s_mov_b32 m0, %0\n\ts_nop 0\n\tglobal_load_lds_dwordx4 %1, %2" :: "s"(_la), "v"(voff), "s"(_gb) : "memory"); } } while (0)
; #define PG8_LDA(dst, b, h) do { _Pragma("unroll") for (int m = 0; m < 4; ++m) _Pragma("unroll") for (int k = 0; k < 2; ++k) dst[m][k] = *(const LAS bf16x8*)(lds + PG8_SA(b, h) + aoff + m * 2048 + k * 1024); } while (0)
; #define PG8_LDB(dst, b, h) do { _Pragma("unroll") for (int n = 0; n < 2; ++n) _Pragma("unroll") for (int k = 0; k < 2; ++k) dst[n][k] = *(const LAS bf16x8*)(lds + PG8_SB(b, h) + boff + n * 2048 + k * 1024); } while (0)
; #define PG8_MMA(ai, bj, At, Bt) do { __builtin_amdgcn_s_setprio(1); _Pragma("unroll") for (int m = 0; m < 4; ++m) _Pragma("unroll") for (int n = 0; n < 2; ++n) _Pragma("unroll") for (int k = 0; k < 2; ++k) \
;         acc[ai][bj][m][n] = __builtin_amdgcn_mfma_f32_16x16x32_bf16(Bt[n][k], At[m][k], acc[ai][bj][m][n], 0, 0, 0); __builtin_amdgcn_s_setprio(0); } while (0)
; #define PG8_WAIT_V(n) asm volatile("s_waitcnt vmcnt(" #n ")" ::: "memory")
; #define PG8_WAIT_L(n) asm volatile("s_waitcnt lgkmcnt(" #n ")" ::: "memory")
; #define PG8_BAR __builtin_amdgcn_s_barrier()
; #define PG8_SCHED __builtin_amdgcn_sched_barrier(0)
; template <class Epi, class Sched>
; __device__ __forceinline__ void gemm_phase(LAS unsigned char* lds, const Sched& S, const Epi& E) {
;     ...
;             PG8_LDB(B0, 0, 0); PG8_LDB(B1, 0, 1); PG8_SCHED; PG8_LDA(At, 0, 0); PG8_STAGE(PG8_SA(1, 1), a1 + hA, voffA, hA / 2);
;             PG8_WAIT_V(8); PG8_WAIT_L(0); PG8_BAR; PG8_MMA(0, 0, At, B0); PG8_MMA(0, 1, At, B1); PG8_BAR; PG8_SCHED;
;             PG8_LDA(At, 0, 1); PG8_STAGE(PG8_SB(0, 0), b2, vB2, hB2 / 2); PG8_STAGE(PG8_SB(0, 1), b2 + hB2, vB2, hB2 / 2); PG8_STAGE(PG8_SA(0, 0), a2, vA2, hA2 / 2);
;             PG8_WAIT_V(8); PG8_WAIT_L(0); PG8_BAR; PG8_MMA(1, 0, At, B0); PG8_MMA(1, 1, At, B1); PG8_BAR; PG8_SCHED;
.LBB0_1484:
	s_add_u32 s24, s24, 0x40080
	s_addc_u32 s25, s25, 0
	s_add_u32 s59, s26, 0x100
	s_addc_u32 s60, s27, 0
	s_mov_b32 s61, -2
	ds_read_b128 v[144:147], v138
	ds_read_b128 v[148:151], v138 offset:1024
	ds_read_b128 v[152:155], v138 offset:2048
	ds_read_b128 v[156:159], v138 offset:3072
	ds_read_b128 v[160:163], v139
	ds_read_b128 v[164:167], v139 offset:1024
	ds_read_b128 v[168:171], v139 offset:2048
	ds_read_b128 v[172:175], v139 offset:3072
	s_add_u32 s26, s24, 0xfffc0080
	s_addc_u32 s27, s25, -1
	s_cmp_eq_u32 s61, 12
	s_cselect_b32 s26, s20, s26
	s_cselect_b32 s27, s21, s27
	s_cselect_b32 s40, s22, s59
	s_cselect_b32 s41, s23, s60
	s_add_u32 s38, s26, 0x80
	s_addc_u32 s39, s27, 0
	ds_read_b128 v[178:181], v140
	ds_read_b128 v[182:185], v140 offset:1024
	ds_read_b128 v[186:189], v140 offset:2048
	ds_read_b128 v[190:193], v140 offset:3072
	ds_read_b128 v[194:197], v140 offset:4096
	ds_read_b128 v[198:201], v140 offset:5120
	ds_read_b128 v[202:205], v140 offset:6144
	ds_read_b128 v[206:209], v140 offset:7168
	s_mov_b32 m0, s54
	s_nop 0
	global_load_lds_dwordx4 v134, s[24:25]
	s_add_u32 s62, s24, 0x20000
	s_mov_b32 m0, s55
	s_addc_u32 s63, s25, 0
	global_load_lds_dwordx4 v134, s[62:63]
	s_add_u32 s62, s24, 0xfffc0000
	s_mov_b32 m0, s50
	s_addc_u32 s63, s25, -1
	global_load_lds_dwordx4 v134, s[62:63]
	s_add_u32 s62, s24, 0xfffe0000
	s_mov_b32 m0, s51
	s_addc_u32 s63, s25, -1
	global_load_lds_dwordx4 v134, s[62:63]
	s_cmp_eq_u32 s19, 0
	s_cbranch_scc1 .Lpeel_strict_42178_0
	s_waitcnt vmcnt(12) lgkmcnt(0)
	s_branch .Lpeel_join_42178_0
.Lpeel_strict_42178_0:
	s_waitcnt vmcnt(4) lgkmcnt(0)
.Lpeel_join_42178_0:
	s_barrier
	v_mfma_f32_16x16x32_bf16 v[124:127], v[144:147], v[178:181], 0
	v_mfma_f32_16x16x32_bf16 v[120:123], v[152:155], v[178:181], 0
	v_mfma_f32_16x16x32_bf16 v[108:111], v[144:147], v[186:189], 0
	v_mfma_f32_16x16x32_bf16 v[104:107], v[152:155], v[186:189], 0
	v_mfma_f32_16x16x32_bf16 v[92:95], v[144:147], v[194:197], 0
	v_mfma_f32_16x16x32_bf16 v[88:91], v[152:155], v[194:197], 0
	v_mfma_f32_16x16x32_bf16 v[76:79], v[144:147], v[202:205], 0
	v_mfma_f32_16x16x32_bf16 v[72:75], v[152:155], v[202:205], 0
	v_mfma_f32_16x16x32_bf16 v[124:127], v[148:151], v[182:185], v[124:127]
	v_mfma_f32_16x16x32_bf16 v[120:123], v[156:159], v[182:185], v[120:123]
	v_mfma_f32_16x16x32_bf16 v[108:111], v[148:151], v[190:193], v[108:111]
	v_mfma_f32_16x16x32_bf16 v[104:107], v[156:159], v[190:193], v[104:107]
	v_mfma_f32_16x16x32_bf16 v[92:95], v[148:151], v[198:201], v[92:95]
	v_mfma_f32_16x16x32_bf16 v[88:91], v[156:159], v[198:201], v[88:91]
	v_mfma_f32_16x16x32_bf16 v[76:79], v[148:151], v[206:209], v[76:79]
	v_mfma_f32_16x16x32_bf16 v[72:75], v[156:159], v[206:209], v[72:75]
	v_mfma_f32_16x16x32_bf16 v[116:119], v[160:163], v[178:181], 0
	v_mfma_f32_16x16x32_bf16 v[112:115], v[168:171], v[178:181], 0
	v_mfma_f32_16x16x32_bf16 v[100:103], v[160:163], v[186:189], 0
	v_mfma_f32_16x16x32_bf16 v[96:99], v[168:171], v[186:189], 0
	v_mfma_f32_16x16x32_bf16 v[84:87], v[160:163], v[194:197], 0
	v_mfma_f32_16x16x32_bf16 v[80:83], v[168:171], v[194:197], 0
	v_mfma_f32_16x16x32_bf16 v[68:71], v[160:163], v[202:205], 0
	v_mfma_f32_16x16x32_bf16 v[64:67], v[168:171], v[202:205], 0
	v_mfma_f32_16x16x32_bf16 v[116:119], v[164:167], v[182:185], v[116:119]
	v_mfma_f32_16x16x32_bf16 v[112:115], v[172:175], v[182:185], v[112:115]
	v_mfma_f32_16x16x32_bf16 v[100:103], v[164:167], v[190:193], v[100:103]
	v_mfma_f32_16x16x32_bf16 v[96:99], v[172:175], v[190:193], v[96:99]
	v_mfma_f32_16x16x32_bf16 v[84:87], v[164:167], v[198:201], v[84:87]
	v_mfma_f32_16x16x32_bf16 v[80:83], v[172:175], v[198:201], v[80:83]
	v_mfma_f32_16x16x32_bf16 v[68:71], v[164:167], v[206:209], v[68:71]
	v_mfma_f32_16x16x32_bf16 v[64:67], v[172:175], v[206:209], v[64:67]
	s_add_i32 s61, s61, 2
	s_add_u32 s24, s24, 0x100
	s_addc_u32 s25, s25, 0
	s_add_u32 s59, s59, 0x100
	s_addc_u32 s60, s60, 0
	s_barrier
	s_add_u32 s62, s40, 0x20000
	ds_read_b128 v[178:181], v140 offset:16384
	ds_read_b128 v[182:185], v140 offset:17408
	ds_read_b128 v[186:189], v140 offset:18432
	ds_read_b128 v[190:193], v140 offset:19456
	ds_read_b128 v[194:197], v140 offset:20480
	ds_read_b128 v[198:201], v140 offset:21504
	ds_read_b128 v[202:205], v140 offset:22528
	ds_read_b128 v[206:209], v140 offset:23552
	s_mov_b32 m0, s36
	s_nop 0
	global_load_lds_dwordx4 v135, s[40:41]
	s_mov_b32 m0, s37
	s_addc_u32 s63, s41, 0
	global_load_lds_dwordx4 v135, s[62:63]
	s_add_u32 s62, s40, 0x40000
	s_mov_b32 m0, s42
	s_addc_u32 s63, s41, 0
	global_load_lds_dwordx4 v135, s[62:63]
	s_add_u32 s62, s40, 0x60000
	s_mov_b32 m0, s43
	s_addc_u32 s63, s41, 0
	global_load_lds_dwordx4 v135, s[62:63]
	s_waitcnt vmcnt(4) lgkmcnt(0)
	s_barrier
	v_mfma_f32_16x16x32_bf16 v[60:63], v[144:147], v[178:181], 0
	v_mfma_f32_16x16x32_bf16 v[56:59], v[152:155], v[178:181], 0
	v_mfma_f32_16x16x32_bf16 v[44:47], v[144:147], v[186:189], 0
	v_mfma_f32_16x16x32_bf16 v[40:43], v[152:155], v[186:189], 0
	v_mfma_f32_16x16x32_bf16 v[28:31], v[144:147], v[194:197], 0
	v_mfma_f32_16x16x32_bf16 v[24:27], v[152:155], v[194:197], 0
	v_mfma_f32_16x16x32_bf16 v[12:15], v[144:147], v[202:205], 0
	v_mfma_f32_16x16x32_bf16 v[8:11], v[152:155], v[202:205], 0
	v_mfma_f32_16x16x32_bf16 v[60:63], v[148:151], v[182:185], v[60:63]
	v_mfma_f32_16x16x32_bf16 v[56:59], v[156:159], v[182:185], v[56:59]
	v_mfma_f32_16x16x32_bf16 v[44:47], v[148:151], v[190:193], v[44:47]
	v_mfma_f32_16x16x32_bf16 v[40:43], v[156:159], v[190:193], v[40:43]
	v_mfma_f32_16x16x32_bf16 v[28:31], v[148:151], v[198:201], v[28:31]
	v_mfma_f32_16x16x32_bf16 v[24:27], v[156:159], v[198:201], v[24:27]
	v_mfma_f32_16x16x32_bf16 v[12:15], v[148:151], v[206:209], v[12:15]
	v_mfma_f32_16x16x32_bf16 v[8:11], v[156:159], v[206:209], v[8:11]
	v_mfma_f32_16x16x32_bf16 v[52:55], v[160:163], v[178:181], 0
	v_mfma_f32_16x16x32_bf16 v[48:51], v[168:171], v[178:181], 0
	v_mfma_f32_16x16x32_bf16 v[36:39], v[160:163], v[186:189], 0
	v_mfma_f32_16x16x32_bf16 v[32:35], v[168:171], v[186:189], 0
	v_mfma_f32_16x16x32_bf16 v[20:23], v[160:163], v[194:197], 0
	v_mfma_f32_16x16x32_bf16 v[16:19], v[168:171], v[194:197], 0
	v_mfma_f32_16x16x32_bf16 v[4:7], v[160:163], v[202:205], 0
	v_mfma_f32_16x16x32_bf16 v[0:3], v[168:171], v[202:205], 0
	v_mfma_f32_16x16x32_bf16 v[52:55], v[164:167], v[182:185], v[52:55]
	v_mfma_f32_16x16x32_bf16 v[48:51], v[172:175], v[182:185], v[48:51]
	v_mfma_f32_16x16x32_bf16 v[36:39], v[164:167], v[190:193], v[36:39]
	v_mfma_f32_16x16x32_bf16 v[32:35], v[172:175], v[190:193], v[32:35]
	v_mfma_f32_16x16x32_bf16 v[20:23], v[164:167], v[198:201], v[20:23]
	v_mfma_f32_16x16x32_bf16 v[16:19], v[172:175], v[198:201], v[16:19]
	v_mfma_f32_16x16x32_bf16 v[4:7], v[164:167], v[206:209], v[4:7]
	v_mfma_f32_16x16x32_bf16 v[0:3], v[172:175], v[206:209], v[0:3]
	s_barrier
	s_branch .Lpeel_mid_42178
; #define PG8_STAGE(bufoff, gbase, voff, p64) do { _Pragma("unroll") for (int _i = 0; _i < 2; ++_i) { \
;         const char* _gb = (const char*)(gbase) + (size_t)_i * (p64); const unsigned _la = ldsbase + (unsigned)(bufoff) + (unsigned)_i * 8192u; \
;         asm volatile("s_mov_b32 m0, %0\n\ts_nop 0\n\tglobal_load_lds_dwordx4 %1, %2" :: "s"(_la), "v"(voff), "s"(_gb) : "memory"); } } while (0)
; #define PG8_LDA(dst, b, h) do { _Pragma("unroll") for (int m = 0; m < 4; ++m) _Pragma("unroll") for (int k = 0; k < 2; ++k) dst[m][k] = *(const LAS bf16x8*)(lds + PG8_SA(b, h) + aoff + m * 2048 + k * 1024); } while (0)
; #define PG8_LDB(dst, b, h) do { _Pragma("unroll") for (int n = 0; n < 2; ++n) _Pragma("unroll") for (int k = 0; k < 2; ++k) dst[n][k] = *(const LAS bf16x8*)(lds + PG8_SB(b, h) + boff + n * 2048 + k * 1024); } while (0)
; #define PG8_MMA(ai, bj, At, Bt) do { __builtin_amdgcn_s_setprio(1); _Pragma("unroll") for (int m = 0; m < 4; ++m) _Pragma("unroll") for (int n = 0; n < 2; ++n) _Pragma("unroll") for (int k = 0; k < 2; ++k) \
;         acc[ai][bj][m][n] = __builtin_amdgcn_mfma_f32_16x16x32_bf16(Bt[n][k], At[m][k], acc[ai][bj][m][n], 0, 0, 0); __builtin_amdgcn_s_setprio(0); } while (0)
; #define PG8_WAIT_V(n) asm volatile("s_waitcnt vmcnt(" #n ")" ::: "memory")
; #define PG8_WAIT_L(n) asm volatile("s_waitcnt lgkmcnt(" #n ")" ::: "memory")
; #define PG8_BAR __builtin_amdgcn_s_barrier()
; #define PG8_SCHED __builtin_amdgcn_sched_barrier(0)
; template <class Epi, class Sched>
; __device__ __forceinline__ void gemm_phase(LAS unsigned char* lds, const Sched& S, const Epi& E) {
;     ...
;             PG8_LDB(B0, 0, 0); PG8_LDB(B1, 0, 1); PG8_SCHED; PG8_LDA(At, 0, 0); PG8_STAGE(PG8_SA(1, 1), a1 + hA, voffA, hA / 2);
;             PG8_WAIT_V(8); PG8_WAIT_L(0); PG8_BAR; PG8_MMA(0, 0, At, B0); PG8_MMA(0, 1, At, B1); PG8_BAR; PG8_SCHED;
;             PG8_LDA(At, 0, 1); PG8_STAGE(PG8_SB(0, 0), b2, vB2, hB2 / 2); PG8_STAGE(PG8_SB(0, 1), b2 + hB2, vB2, hB2 / 2); PG8_STAGE(PG8_SA(0, 0), a2, vA2, hA2 / 2);
;             PG8_WAIT_V(8); PG8_WAIT_L(0); PG8_BAR; PG8_MMA(1, 0, At, B0); PG8_MMA(1, 1, At, B1); PG8_BAR; PG8_SCHED;
.LBB0_1485:
	ds_read_b128 v[144:147], v138
	ds_read_b128 v[148:151], v138 offset:1024
	ds_read_b128 v[152:155], v138 offset:2048
	ds_read_b128 v[156:159], v138 offset:3072
	ds_read_b128 v[160:163], v139
	ds_read_b128 v[164:167], v139 offset:1024
	ds_read_b128 v[168:171], v139 offset:2048
	ds_read_b128 v[172:175], v139 offset:3072
	s_add_u32 s26, s24, 0xfffc0080
	s_addc_u32 s27, s25, -1
	s_cmp_eq_u32 s61, 12
	s_cselect_b32 s26, s20, s26
	s_cselect_b32 s27, s21, s27
	s_cselect_b32 s40, s22, s59
	s_cselect_b32 s41, s23, s60
	s_add_u32 s38, s26, 0x80
	s_addc_u32 s39, s27, 0
	ds_read_b128 v[178:181], v140
	ds_read_b128 v[182:185], v140 offset:1024
	ds_read_b128 v[186:189], v140 offset:2048
	ds_read_b128 v[190:193], v140 offset:3072
	ds_read_b128 v[194:197], v140 offset:4096
	ds_read_b128 v[198:201], v140 offset:5120
	ds_read_b128 v[202:205], v140 offset:6144
	ds_read_b128 v[206:209], v140 offset:7168
	s_mov_b32 m0, s54
	s_nop 0
	global_load_lds_dwordx4 v134, s[24:25]
	s_add_u32 s62, s24, 0x20000
	s_mov_b32 m0, s55
	s_addc_u32 s63, s25, 0
	global_load_lds_dwordx4 v134, s[62:63]
	s_add_u32 s62, s24, 0xfffc0000
	s_mov_b32 m0, s50
	s_addc_u32 s63, s25, -1
	global_load_lds_dwordx4 v134, s[62:63]
	s_add_u32 s62, s24, 0xfffe0000
	s_mov_b32 m0, s51
	s_addc_u32 s63, s25, -1
	global_load_lds_dwordx4 v134, s[62:63]
	s_waitcnt vmcnt(4) lgkmcnt(0)
	s_barrier
	v_mfma_f32_16x16x32_bf16 v[124:127], v[144:147], v[178:181], v[124:127]
	v_mfma_f32_16x16x32_bf16 v[120:123], v[152:155], v[178:181], v[120:123]
	v_mfma_f32_16x16x32_bf16 v[108:111], v[144:147], v[186:189], v[108:111]
	v_mfma_f32_16x16x32_bf16 v[104:107], v[152:155], v[186:189], v[104:107]
	v_mfma_f32_16x16x32_bf16 v[92:95], v[144:147], v[194:197], v[92:95]
	v_mfma_f32_16x16x32_bf16 v[88:91], v[152:155], v[194:197], v[88:91]
	v_mfma_f32_16x16x32_bf16 v[76:79], v[144:147], v[202:205], v[76:79]
	v_mfma_f32_16x16x32_bf16 v[72:75], v[152:155], v[202:205], v[72:75]
	v_mfma_f32_16x16x32_bf16 v[124:127], v[148:151], v[182:185], v[124:127]
	v_mfma_f32_16x16x32_bf16 v[120:123], v[156:159], v[182:185], v[120:123]
	v_mfma_f32_16x16x32_bf16 v[108:111], v[148:151], v[190:193], v[108:111]
	v_mfma_f32_16x16x32_bf16 v[104:107], v[156:159], v[190:193], v[104:107]
	v_mfma_f32_16x16x32_bf16 v[92:95], v[148:151], v[198:201], v[92:95]
	v_mfma_f32_16x16x32_bf16 v[88:91], v[156:159], v[198:201], v[88:91]
	v_mfma_f32_16x16x32_bf16 v[76:79], v[148:151], v[206:209], v[76:79]
	v_mfma_f32_16x16x32_bf16 v[72:75], v[156:159], v[206:209], v[72:75]
	v_mfma_f32_16x16x32_bf16 v[116:119], v[160:163], v[178:181], v[116:119]
	v_mfma_f32_16x16x32_bf16 v[112:115], v[168:171], v[178:181], v[112:115]
	v_mfma_f32_16x16x32_bf16 v[100:103], v[160:163], v[186:189], v[100:103]
	v_mfma_f32_16x16x32_bf16 v[96:99], v[168:171], v[186:189], v[96:99]
	v_mfma_f32_16x16x32_bf16 v[84:87], v[160:163], v[194:197], v[84:87]
	v_mfma_f32_16x16x32_bf16 v[80:83], v[168:171], v[194:197], v[80:83]
	v_mfma_f32_16x16x32_bf16 v[68:71], v[160:163], v[202:205], v[68:71]
	v_mfma_f32_16x16x32_bf16 v[64:67], v[168:171], v[202:205], v[64:67]
	v_mfma_f32_16x16x32_bf16 v[116:119], v[164:167], v[182:185], v[116:119]
	v_mfma_f32_16x16x32_bf16 v[112:115], v[172:175], v[182:185], v[112:115]
	v_mfma_f32_16x16x32_bf16 v[100:103], v[164:167], v[190:193], v[100:103]
	v_mfma_f32_16x16x32_bf16 v[96:99], v[172:175], v[190:193], v[96:99]
	v_mfma_f32_16x16x32_bf16 v[84:87], v[164:167], v[198:201], v[84:87]
	v_mfma_f32_16x16x32_bf16 v[80:83], v[172:175], v[198:201], v[80:83]
	v_mfma_f32_16x16x32_bf16 v[68:71], v[164:167], v[206:209], v[68:71]
	v_mfma_f32_16x16x32_bf16 v[64:67], v[172:175], v[206:209], v[64:67]
	s_add_i32 s61, s61, 2
	s_add_u32 s24, s24, 0x100
	s_addc_u32 s25, s25, 0
	s_add_u32 s59, s59, 0x100
	s_addc_u32 s60, s60, 0
	s_barrier
	s_add_u32 s62, s40, 0x20000
	ds_read_b128 v[178:181], v140 offset:16384
	ds_read_b128 v[182:185], v140 offset:17408
	ds_read_b128 v[186:189], v140 offset:18432
	ds_read_b128 v[190:193], v140 offset:19456
	ds_read_b128 v[194:197], v140 offset:20480
	ds_read_b128 v[198:201], v140 offset:21504
	ds_read_b128 v[202:205], v140 offset:22528
	ds_read_b128 v[206:209], v140 offset:23552
	s_mov_b32 m0, s36
	s_nop 0
	global_load_lds_dwordx4 v135, s[40:41]
	s_mov_b32 m0, s37
	s_addc_u32 s63, s41, 0
	global_load_lds_dwordx4 v135, s[62:63]
	s_add_u32 s62, s40, 0x40000
	s_mov_b32 m0, s42
	s_addc_u32 s63, s41, 0
	global_load_lds_dwordx4 v135, s[62:63]
	s_add_u32 s62, s40, 0x60000
	s_mov_b32 m0, s43
	s_addc_u32 s63, s41, 0
	global_load_lds_dwordx4 v135, s[62:63]
	s_waitcnt vmcnt(4) lgkmcnt(0)
	s_barrier
	v_mfma_f32_16x16x32_bf16 v[60:63], v[144:147], v[178:181], v[60:63]
	v_mfma_f32_16x16x32_bf16 v[56:59], v[152:155], v[178:181], v[56:59]
	v_mfma_f32_16x16x32_bf16 v[44:47], v[144:147], v[186:189], v[44:47]
	v_mfma_f32_16x16x32_bf16 v[40:43], v[152:155], v[186:189], v[40:43]
	v_mfma_f32_16x16x32_bf16 v[28:31], v[144:147], v[194:197], v[28:31]
	v_mfma_f32_16x16x32_bf16 v[24:27], v[152:155], v[194:197], v[24:27]
	v_mfma_f32_16x16x32_bf16 v[12:15], v[144:147], v[202:205], v[12:15]
	v_mfma_f32_16x16x32_bf16 v[8:11], v[152:155], v[202:205], v[8:11]
	v_mfma_f32_16x16x32_bf16 v[60:63], v[148:151], v[182:185], v[60:63]
	v_mfma_f32_16x16x32_bf16 v[56:59], v[156:159], v[182:185], v[56:59]
	v_mfma_f32_16x16x32_bf16 v[44:47], v[148:151], v[190:193], v[44:47]
	v_mfma_f32_16x16x32_bf16 v[40:43], v[156:159], v[190:193], v[40:43]
	v_mfma_f32_16x16x32_bf16 v[28:31], v[148:151], v[198:201], v[28:31]
	v_mfma_f32_16x16x32_bf16 v[24:27], v[156:159], v[198:201], v[24:27]
	v_mfma_f32_16x16x32_bf16 v[12:15], v[148:151], v[206:209], v[12:15]
	v_mfma_f32_16x16x32_bf16 v[8:11], v[156:159], v[206:209], v[8:11]
	v_mfma_f32_16x16x32_bf16 v[52:55], v[160:163], v[178:181], v[52:55]
	v_mfma_f32_16x16x32_bf16 v[48:51], v[168:171], v[178:181], v[48:51]
	v_mfma_f32_16x16x32_bf16 v[36:39], v[160:163], v[186:189], v[36:39]
	v_mfma_f32_16x16x32_bf16 v[32:35], v[168:171], v[186:189], v[32:35]
	v_mfma_f32_16x16x32_bf16 v[20:23], v[160:163], v[194:197], v[20:23]
	v_mfma_f32_16x16x32_bf16 v[16:19], v[168:171], v[194:197], v[16:19]
	v_mfma_f32_16x16x32_bf16 v[4:7], v[160:163], v[202:205], v[4:7]
	v_mfma_f32_16x16x32_bf16 v[0:3], v[168:171], v[202:205], v[0:3]
	v_mfma_f32_16x16x32_bf16 v[52:55], v[164:167], v[182:185], v[52:55]
	v_mfma_f32_16x16x32_bf16 v[48:51], v[172:175], v[182:185], v[48:51]
	v_mfma_f32_16x16x32_bf16 v[36:39], v[164:167], v[190:193], v[36:39]
	v_mfma_f32_16x16x32_bf16 v[32:35], v[172:175], v[190:193], v[32:35]
	v_mfma_f32_16x16x32_bf16 v[20:23], v[164:167], v[198:201], v[20:23]
	v_mfma_f32_16x16x32_bf16 v[16:19], v[172:175], v[198:201], v[16:19]
	v_mfma_f32_16x16x32_bf16 v[4:7], v[164:167], v[206:209], v[4:7]
	v_mfma_f32_16x16x32_bf16 v[0:3], v[172:175], v[206:209], v[0:3]
	s_barrier
; #define PG8_STAGE(bufoff, gbase, voff, p64) do { _Pragma("unroll") for (int _i = 0; _i < 2; ++_i) { \
;         const char* _gb = (const char*)(gbase) + (size_t)_i * (p64); const unsigned _la = ldsbase + (unsigned)(bufoff) + (unsigned)_i * 8192u; \
;         asm volatile("s_mov_b32 m0, %0\n\ts_nop 0\n\tglobal_load_lds_dwordx4 %1, %2" :: "s"(_la), "v"(voff), "s"(_gb) : "memory"); } } while (0)
; #define PG8_LDA(dst, b, h) do { _Pragma("unroll") for (int m = 0; m < 4; ++m) _Pragma("unroll") for (int k = 0; k < 2; ++k) dst[m][k] = *(const LAS bf16x8*)(lds + PG8_SA(b, h) + aoff + m * 2048 + k * 1024); } while (0)
; #define PG8_LDB(dst, b, h) do { _Pragma("unroll") for (int n = 0; n < 2; ++n) _Pragma("unroll") for (int k = 0; k < 2; ++k) dst[n][k] = *(const LAS bf16x8*)(lds + PG8_SB(b, h) + boff + n * 2048 + k * 1024); } while (0)
; #define PG8_MMA(ai, bj, At, Bt) do { __builtin_amdgcn_s_setprio(1); _Pragma("unroll") for (int m = 0; m < 4; ++m) _Pragma("unroll") for (int n = 0; n < 2; ++n) _Pragma("unroll") for (int k = 0; k < 2; ++k) \
;         acc[ai][bj][m][n] = __builtin_amdgcn_mfma_f32_16x16x32_bf16(Bt[n][k], At[m][k], acc[ai][bj][m][n], 0, 0, 0); __builtin_amdgcn_s_setprio(0); } while (0)
; #define PG8_WAIT_V(n) asm volatile("s_waitcnt vmcnt(" #n ")" ::: "memory")
; #define PG8_WAIT_L(n) asm volatile("s_waitcnt lgkmcnt(" #n ")" ::: "memory")
; #define PG8_BAR __builtin_amdgcn_s_barrier()
; #define PG8_SCHED __builtin_amdgcn_sched_barrier(0)
; template <class Epi, class Sched>
; __device__ __forceinline__ void gemm_phase(LAS unsigned char* lds, const Sched& S, const Epi& E) {
;     ...
;             PG8_LDB(B0, 1, 0); PG8_LDB(B1, 1, 1); PG8_SCHED; PG8_LDA(At, 1, 0); PG8_STAGE(PG8_SA(0, 1), a2 + hA2, vA2, hA2 / 2);
;             PG8_WAIT_V(8); PG8_WAIT_L(0); PG8_BAR; PG8_MMA(0, 0, At, B0); PG8_MMA(0, 1, At, B1); PG8_BAR; PG8_SCHED;
;             PG8_LDA(At, 1, 1); PG8_STAGE(PG8_SB(1, 0), b3, vB2, hB2 / 2); PG8_STAGE(PG8_SB(1, 1), b3 + hB2, vB2, hB2 / 2); PG8_STAGE(PG8_SA(1, 0), a3, vA2, hA2 / 2);
;             PG8_WAIT_V(8); PG8_WAIT_L(0); PG8_BAR; PG8_MMA(1, 0, At, B0); PG8_MMA(1, 1, At, B1); PG8_BAR; PG8_SCHED;
.Lpeel_mid_42178:
	ds_read_b128 v[144:147], v141
	ds_read_b128 v[148:151], v141 offset:1024
	ds_read_b128 v[152:155], v141 offset:2048
	ds_read_b128 v[156:159], v141 offset:3072
	ds_read_b128 v[160:163], v142
	ds_read_b128 v[164:167], v142 offset:1024
	ds_read_b128 v[168:171], v142 offset:2048
	ds_read_b128 v[172:175], v142 offset:3072
	ds_read_b128 v[178:181], v140 offset:32768
	ds_read_b128 v[182:185], v140 offset:33792
	ds_read_b128 v[186:189], v140 offset:34816
	ds_read_b128 v[190:193], v140 offset:35840
	ds_read_b128 v[194:197], v140 offset:36864
	ds_read_b128 v[198:201], v140 offset:37888
	ds_read_b128 v[202:205], v140 offset:38912
	ds_read_b128 v[206:209], v140 offset:39936
	s_add_u32 s62, s26, 0x40000
	s_mov_b32 m0, s45
	s_addc_u32 s63, s27, 0
	global_load_lds_dwordx4 v134, s[62:63]
	s_add_u32 s62, s26, 0x60000
	s_mov_b32 m0, s46
	s_addc_u32 s63, s27, 0
	global_load_lds_dwordx4 v134, s[62:63]
	s_mov_b32 m0, s34
	s_nop 0
	global_load_lds_dwordx4 v134, s[26:27]
	s_add_u32 s62, s26, 0x20000
	s_mov_b32 m0, s44
	s_addc_u32 s63, s27, 0
	global_load_lds_dwordx4 v134, s[62:63]
	s_waitcnt vmcnt(4) lgkmcnt(0)
	s_barrier
	v_mfma_f32_16x16x32_bf16 v[124:127], v[144:147], v[178:181], v[124:127]
	v_mfma_f32_16x16x32_bf16 v[120:123], v[152:155], v[178:181], v[120:123]
	v_mfma_f32_16x16x32_bf16 v[108:111], v[144:147], v[186:189], v[108:111]
	v_mfma_f32_16x16x32_bf16 v[104:107], v[152:155], v[186:189], v[104:107]
	v_mfma_f32_16x16x32_bf16 v[92:95], v[144:147], v[194:197], v[92:95]
	v_mfma_f32_16x16x32_bf16 v[88:91], v[152:155], v[194:197], v[88:91]
	v_mfma_f32_16x16x32_bf16 v[76:79], v[144:147], v[202:205], v[76:79]
	v_mfma_f32_16x16x32_bf16 v[72:75], v[152:155], v[202:205], v[72:75]
	v_mfma_f32_16x16x32_bf16 v[124:127], v[148:151], v[182:185], v[124:127]
	v_mfma_f32_16x16x32_bf16 v[120:123], v[156:159], v[182:185], v[120:123]
	v_mfma_f32_16x16x32_bf16 v[108:111], v[148:151], v[190:193], v[108:111]
	v_mfma_f32_16x16x32_bf16 v[104:107], v[156:159], v[190:193], v[104:107]
	v_mfma_f32_16x16x32_bf16 v[92:95], v[148:151], v[198:201], v[92:95]
	v_mfma_f32_16x16x32_bf16 v[88:91], v[156:159], v[198:201], v[88:91]
	v_mfma_f32_16x16x32_bf16 v[76:79], v[148:151], v[206:209], v[76:79]
	v_mfma_f32_16x16x32_bf16 v[72:75], v[156:159], v[206:209], v[72:75]
	v_mfma_f32_16x16x32_bf16 v[116:119], v[160:163], v[178:181], v[116:119]
	v_mfma_f32_16x16x32_bf16 v[112:115], v[168:171], v[178:181], v[112:115]
	v_mfma_f32_16x16x32_bf16 v[100:103], v[160:163], v[186:189], v[100:103]
	v_mfma_f32_16x16x32_bf16 v[96:99], v[168:171], v[186:189], v[96:99]
	v_mfma_f32_16x16x32_bf16 v[84:87], v[160:163], v[194:197], v[84:87]
	v_mfma_f32_16x16x32_bf16 v[80:83], v[168:171], v[194:197], v[80:83]
	v_mfma_f32_16x16x32_bf16 v[68:71], v[160:163], v[202:205], v[68:71]
	v_mfma_f32_16x16x32_bf16 v[64:67], v[168:171], v[202:205], v[64:67]
	v_mfma_f32_16x16x32_bf16 v[116:119], v[164:167], v[182:185], v[116:119]
	v_mfma_f32_16x16x32_bf16 v[112:115], v[172:175], v[182:185], v[112:115]
	v_mfma_f32_16x16x32_bf16 v[100:103], v[164:167], v[190:193], v[100:103]
	v_mfma_f32_16x16x32_bf16 v[96:99], v[172:175], v[190:193], v[96:99]
	v_mfma_f32_16x16x32_bf16 v[84:87], v[164:167], v[198:201], v[84:87]
	v_mfma_f32_16x16x32_bf16 v[80:83], v[172:175], v[198:201], v[80:83]
	v_mfma_f32_16x16x32_bf16 v[68:71], v[164:167], v[206:209], v[68:71]
	v_mfma_f32_16x16x32_bf16 v[64:67], v[172:175], v[206:209], v[64:67]
	s_barrier
	s_add_u32 s62, s40, 0x80
	s_addc_u32 s63, s41, 0
	ds_read_b128 v[178:181], v140 offset:49152
	ds_read_b128 v[182:185], v140 offset:50176
	ds_read_b128 v[186:189], v140 offset:51200
	ds_read_b128 v[190:193], v140 offset:52224
	ds_read_b128 v[194:197], v140 offset:53248
	ds_read_b128 v[198:201], v140 offset:54272
	ds_read_b128 v[202:205], v140 offset:55296
	ds_read_b128 v[206:209], v140 offset:56320
	s_mov_b32 m0, s48
	s_nop 0
	global_load_lds_dwordx4 v135, s[62:63]
	s_add_u32 s62, s40, 0x20080
	s_mov_b32 m0, s49
	s_addc_u32 s63, s41, 0
	global_load_lds_dwordx4 v135, s[62:63]
	s_add_u32 s62, s40, 0x40080
	s_mov_b32 m0, s52
	s_addc_u32 s63, s41, 0
	global_load_lds_dwordx4 v135, s[62:63]
	s_add_u32 s40, s40, 0x60080
	s_mov_b32 m0, s53
	s_addc_u32 s41, s41, 0
	global_load_lds_dwordx4 v135, s[40:41]
	s_waitcnt vmcnt(4) lgkmcnt(0)
	s_barrier
	v_mfma_f32_16x16x32_bf16 v[60:63], v[144:147], v[178:181], v[60:63]
	v_mfma_f32_16x16x32_bf16 v[56:59], v[152:155], v[178:181], v[56:59]
	v_mfma_f32_16x16x32_bf16 v[44:47], v[144:147], v[186:189], v[44:47]
	v_mfma_f32_16x16x32_bf16 v[40:43], v[152:155], v[186:189], v[40:43]
	v_mfma_f32_16x16x32_bf16 v[28:31], v[144:147], v[194:197], v[28:31]
	v_mfma_f32_16x16x32_bf16 v[24:27], v[152:155], v[194:197], v[24:27]
	v_mfma_f32_16x16x32_bf16 v[12:15], v[144:147], v[202:205], v[12:15]
	v_mfma_f32_16x16x32_bf16 v[8:11], v[152:155], v[202:205], v[8:11]
	v_mfma_f32_16x16x32_bf16 v[60:63], v[148:151], v[182:185], v[60:63]
	v_mfma_f32_16x16x32_bf16 v[56:59], v[156:159], v[182:185], v[56:59]
	v_mfma_f32_16x16x32_bf16 v[44:47], v[148:151], v[190:193], v[44:47]
	v_mfma_f32_16x16x32_bf16 v[40:43], v[156:159], v[190:193], v[40:43]
	v_mfma_f32_16x16x32_bf16 v[28:31], v[148:151], v[198:201], v[28:31]
	v_mfma_f32_16x16x32_bf16 v[24:27], v[156:159], v[198:201], v[24:27]
	v_mfma_f32_16x16x32_bf16 v[12:15], v[148:151], v[206:209], v[12:15]
	v_mfma_f32_16x16x32_bf16 v[8:11], v[156:159], v[206:209], v[8:11]
	v_mfma_f32_16x16x32_bf16 v[52:55], v[160:163], v[178:181], v[52:55]
	v_mfma_f32_16x16x32_bf16 v[48:51], v[168:171], v[178:181], v[48:51]
	v_mfma_f32_16x16x32_bf16 v[36:39], v[160:163], v[186:189], v[36:39]
	v_mfma_f32_16x16x32_bf16 v[32:35], v[168:171], v[186:189], v[32:35]
	v_mfma_f32_16x16x32_bf16 v[20:23], v[160:163], v[194:197], v[20:23]
	v_mfma_f32_16x16x32_bf16 v[16:19], v[168:171], v[194:197], v[16:19]
	v_mfma_f32_16x16x32_bf16 v[4:7], v[160:163], v[202:205], v[4:7]
	v_mfma_f32_16x16x32_bf16 v[0:3], v[168:171], v[202:205], v[0:3]
	v_mfma_f32_16x16x32_bf16 v[52:55], v[164:167], v[182:185], v[52:55]
	v_mfma_f32_16x16x32_bf16 v[48:51], v[172:175], v[182:185], v[48:51]
	v_mfma_f32_16x16x32_bf16 v[36:39], v[164:167], v[190:193], v[36:39]
	v_mfma_f32_16x16x32_bf16 v[32:35], v[172:175], v[190:193], v[32:35]
	v_mfma_f32_16x16x32_bf16 v[20:23], v[164:167], v[198:201], v[20:23]
	v_mfma_f32_16x16x32_bf16 v[16:19], v[172:175], v[198:201], v[16:19]
	v_mfma_f32_16x16x32_bf16 v[4:7], v[164:167], v[206:209], v[4:7]
	v_mfma_f32_16x16x32_bf16 v[0:3], v[172:175], v[206:209], v[0:3]
	s_barrier
	s_cmp_gt_u32 s61, 13
	s_cbranch_scc0 .LBB0_1485
	s_and_b64 vcc, exec, s[14:15]
	s_cbranch_vccz .LBB0_1488
	s_barrier
